# attention K tile staged by LDS-DMA (global_load_lds_dwordx4, 13 per tile incl. pad slots) instead of global_load + v_mov + ds_write_b128; V stays register-staged
# speedup vs baseline: 1.0085x; 1.0031x over previous
.LBB0_727:
	s_or_b64 exec, exec, s[44:45]
	s_ashr_i32 s64, s47, 1
	s_andn2_b32 s64, s64, 31
	s_lshl_b32 s44, s46, 7
	v_lshl_add_u32 v224, s64, 1, v176
	v_mov_b32_e32 v235, 0x20000
	v_mov_b32_e32 v234, 0x1000
	v_mov_b32_e32 v236, s10
	v_mov_b32_e32 v237, s11
	v_mov_b32_e32 v238, s6
	v_mov_b32_e32 v239, s7
	v_mul_u32_u24_e32 v226, 0x4ec5, v224
	v_lshrrev_b32_e32 v226, 18, v226
	v_mul_u32_u24_e32 v227, 13, v226
	v_sub_u32_e32 v227, v224, v227
	v_min_u32_e32 v227, 11, v227
	v_add_u32_e32 v226, s50, v226
	v_lshlrev_b32_e32 v228, 4, v227
	v_lshlrev_b32_e32 v230, 11, v226
	v_add3_u32 v230, v230, v228, s44
	v_lshlrev_b32_e32 v231, 6, v226
	v_add_u32_e32 v231, v231, v228
	v_add_u32_e32 v231, 0xffffff80, v231
	v_cmp_gt_u32_e32 vcc, 8, v227
	s_nop 1
	v_cndmask_b32_e32 v232, v231, v230, vcc
	v_mov_b32_e32 v233, 0
	v_cndmask_b32_e32 v240, v236, v238, vcc
	v_cndmask_b32_e32 v241, v237, v239, vcc
	v_cndmask_b32_e32 v220, v234, v235, vcc
	v_mov_b32_e32 v221, 0
	v_lshl_add_u64 v[204:205], v[232:233], 0, v[240:241]
	v_lshl_add_u64 v[204:205], v[220:221], 1, v[204:205]
	v_add_u32_e32 v225, 64, v224
	v_mul_u32_u24_e32 v226, 0x4ec5, v225
	v_lshrrev_b32_e32 v226, 18, v226
	v_mul_u32_u24_e32 v227, 13, v226
	v_sub_u32_e32 v227, v225, v227
	v_min_u32_e32 v227, 11, v227
	v_add_u32_e32 v226, s50, v226
	v_lshlrev_b32_e32 v228, 4, v227
	v_lshlrev_b32_e32 v230, 11, v226
	v_add3_u32 v230, v230, v228, s44
	v_lshlrev_b32_e32 v231, 6, v226
	v_add_u32_e32 v231, v231, v228
	v_add_u32_e32 v231, 0xffffff80, v231
	v_cmp_gt_u32_e32 vcc, 8, v227
	s_nop 1
	v_cndmask_b32_e32 v232, v231, v230, vcc
	v_mov_b32_e32 v233, 0
	v_cndmask_b32_e32 v240, v236, v238, vcc
	v_cndmask_b32_e32 v241, v237, v239, vcc
	v_cndmask_b32_e32 v222, v234, v235, vcc
	v_mov_b32_e32 v223, 0
	v_lshl_add_u64 v[206:207], v[232:233], 0, v[240:241]
	v_lshl_add_u64 v[206:207], v[222:223], 1, v[206:207]
	s_cmp_gt_i32 s66, -1
	s_cselect_b64 s[48:49], -1, 0
	s_and_b64 s[44:45], s[48:49], exec
	s_cselect_b32 s16, s64, 0
	v_and_b32_e32 v186, 31, v8
	s_add_i32 s16, s16, s63
	v_add_u32_e32 v2, s16, v186
	v_mov_b64_e32 v[0:1], s[4:5]
	v_bfe_u32 v185, v8, 5, 1
	v_mad_i64_i32 v[0:1], s[44:45], v2, s25, v[0:1]
	s_mul_i32 s16, s46, 0xc0
	v_lshl_add_u64 v[0:1], v[0:1], 0, s[16:17]
	v_lshlrev_b32_e32 v166, 4, v185
	v_mov_b32_e32 v167, v81
	v_lshl_add_u64 v[0:1], v[0:1], 0, v[166:167]
	global_load_dwordx4 v[104:107], v[0:1], off
	global_load_dwordx4 v[100:103], v[0:1], off offset:32
	global_load_dwordx4 v[96:99], v[0:1], off offset:64
	global_load_dwordx4 v[92:95], v[0:1], off offset:96
	global_load_dwordx4 v[88:91], v[0:1], off offset:128
	global_load_dwordx4 v[84:87], v[0:1], off offset:160
	s_nop 0
	global_load_dwordx4 v[0:3], v[124:125], off
	v_mov_b32_e32 v80, v81
	s_movk_i32 s16, 0x100
	v_mov_b32_e32 v82, v81
	v_mov_b32_e32 v83, v81
	v_mov_b64_e32 v[4:5], v[80:81]
	v_cmp_gt_i32_e64 s[44:45], s16, v8
	v_mov_b64_e32 v[6:7], v[82:83]
	s_and_saveexec_b64 s[46:47], s[44:45]
	s_cbranch_execz .LBB0_729
	global_load_dwordx4 v[4:7], v[128:129], off

.LBB0_739:
	s_or_b64 exec, exec, s[46:47]
	s_lshl_b32 s16, s64, 2
	s_add_i32 s16, s16, 0
	s_lshl_b64 s[50:51], s[50:51], 1
	v_mad_i64_i32 v[48:49], s[46:47], v127, s37, 0
	v_mov_b32_e32 v133, v81
	s_add_u32 s50, s14, s50
	v_lshl_add_u64 v[48:49], v[48:49], 0, v[132:133]
	s_addc_u32 s51, s15, s51
	s_waitcnt vmcnt(1)
	v_mov_b64_e32 v[122:123], v[110:111]
	s_mov_b32 s67, 0
	v_cmp_eq_u32_e64 s[46:47], 0, v185
	v_lshl_add_u32 v190, v186, 2, s16
	v_mad_u64_u32 v[170:171], s[68:69], v130, 6, v[128:129]
	v_mov_b32_e32 v169, v81
	v_lshl_add_u64 v[172:173], s[50:51], 0, v[48:49]
	v_mad_u64_u32 v[174:175], s[50:51], v126, 6, v[124:125]
	v_mov_b64_e32 v[120:121], v[108:109]
	v_add_u32_e32 v191, 0x2400, v188
	ds_write2_b64 v191, v[56:57], v[58:59] offset1:2
	s_waitcnt lgkmcnt(0)
	s_barrier
	s_waitcnt vmcnt(0)
	s_branch .Latt_top2
.LBB0_740:
	v_mov_b64_e32 v[116:117], v[128:129]
	v_mov_b64_e32 v[118:119], v[130:131]
.Latt_top2:
	global_load_dwordx4 v[128:131], v[172:173], off
	s_add_i32 s67, s67, 1
	s_and_b32 s68, s67, 1
	s_cmpk_ge_u32 s64, 0xe0
	s_cbranch_scc1 .Lkdma_done_l
	s_xor_b32 s69, s68, 1
	s_mul_i32 s69, s69, 0x3400
	s_lshl_b32 s50, s64, 6
	s_add_i32 s69, s69, s50
	s_mov_b32 m0, s69
	s_nop 0
	global_load_lds_dwordx4 v[204:205], off
	v_lshl_add_u64 v[204:205], v[204:205], 0, v[220:221]
	s_cmpk_ge_u32 s64, 0xc0
	s_cbranch_scc1 .Lkdma_done_l
	s_add_i32 m0, s69, 0x400
	s_nop 0
	global_load_lds_dwordx4 v[206:207], off
	v_lshl_add_u64 v[206:207], v[206:207], 0, v[222:223]
.Lkdma_done_l:
	s_cmp_gt_i32 s67, s66
	s_cbranch_scc1 .Latt_wonly
	s_mul_i32 s50, s68, 0x3400
	v_add_u32_e32 v52, s50, v189
	ds_read_b128 v[48:51], v52
	ds_read_b128 v[132:135], v52 offset:32
	ds_read_b128 v[136:139], v52 offset:6656
	ds_read_b128 v[140:143], v52 offset:6688
	ds_read_b128 v[144:147], v52 offset:64
	ds_read_b128 v[148:151], v52 offset:96
	ds_read_b128 v[152:155], v52 offset:6720
	ds_read_b128 v[156:159], v52 offset:6752
	ds_read_b128 v[160:163], v52 offset:128
	ds_read_b128 v[192:195], v52 offset:160
	ds_read_b128 v[196:199], v52 offset:6784
	ds_read_b128 v[200:203], v52 offset:6816
	s_waitcnt lgkmcnt(11)
	v_mfma_f32_32x32x16_bf16 v[64:79], v[48:51], v[104:107], v[32:47]
	s_mul_i32 s50, s68, 0x2400
	s_waitcnt lgkmcnt(9)
	v_mfma_f32_32x32x16_bf16 v[48:63], v[136:139], v[104:107], v[32:47]
	v_mfma_f32_32x32x16_bf16 v[64:79], v[132:135], v[100:103], v[64:79]
	v_add_u32_e32 v132, s50, v165
	v_add_u32_e32 v133, 0x6800, v132
	v_add_u32_e32 v132, 0x7800, v132
	s_waitcnt lgkmcnt(8)
	v_mfma_f32_32x32x16_bf16 v[48:63], v[140:143], v[100:103], v[48:63]
	s_waitcnt lgkmcnt(7)
	v_mfma_f32_32x32x16_bf16 v[64:79], v[144:147], v[96:99], v[64:79]
	s_waitcnt lgkmcnt(5)
	v_mfma_f32_32x32x16_bf16 v[48:63], v[152:155], v[96:99], v[48:63]
	ds_read_b128 v[152:155], v133 offset:32
	v_mfma_f32_32x32x16_bf16 v[64:79], v[148:151], v[92:95], v[64:79]
	s_waitcnt lgkmcnt(5)
	v_mfma_f32_32x32x16_bf16 v[48:63], v[156:159], v[92:95], v[48:63]
	s_waitcnt lgkmcnt(4)
	v_mfma_f32_32x32x16_bf16 v[64:79], v[160:163], v[88:91], v[64:79]
	ds_read_b128 v[160:163], v133
	ds_read_b128 v[156:159], v132 offset:512
	ds_read_b128 v[148:151], v132 offset:544
	ds_read_b128 v[144:147], v133 offset:64
	ds_read_b128 v[140:143], v132 offset:576
	ds_read_b128 v[136:139], v133 offset:96
	ds_read_b128 v[132:135], v132 offset:608
	s_waitcnt lgkmcnt(9)
	v_mfma_f32_32x32x16_bf16 v[48:63], v[196:199], v[88:91], v[48:63]
	v_mfma_f32_32x32x16_bf16 v[64:79], v[192:195], v[84:87], v[64:79]
	s_waitcnt lgkmcnt(8)
	v_mfma_f32_32x32x16_bf16 v[48:63], v[200:203], v[84:87], v[48:63]
	s_xor_b32 s68, s68, 1
	s_mulk_i32 s68, 0x2400
	v_add_u32_e32 v191, s68, v188
	v_lshl_add_u64 v[172:173], v[172:173], 0, s[18:19]
	ds_write2_b64 v191, v[116:117], v[118:119] offset1:2
	s_nop 7
	v_max_f32_e32 v191, v65, v65
	v_max_f32_e32 v192, v64, v64
	v_max_f32_e32 v191, v192, v191
	v_max3_f32 v192, v66, v67, v49
	v_max3_f32 v191, v191, v48, v50
	v_max3_f32 v191, v191, v51, v68
	v_max3_f32 v192, v192, v70, v71
	v_max3_f32 v191, v191, v69, v52
	v_max3_f32 v192, v192, v54, v55
	v_max3_f32 v191, v191, v53, v72
	v_max3_f32 v192, v192, v74, v75
	v_max3_f32 v191, v191, v73, v56
	v_max3_f32 v192, v192, v58, v59
	v_max3_f32 v191, v191, v57, v76
	v_max3_f32 v192, v192, v78, v79
	v_max3_f32 v191, v191, v77, v60
	v_max3_f32 v192, v192, v62, v63
	v_max3_f32 v191, v191, v61, v192
	v_mov_b32_e32 v192, v191
	s_nop 1
	v_permlane32_swap_b32_e32 v191, v192
	v_max_f32_e32 v191, v191, v192
	v_cmp_lt_f32_e32 vcc, s3, v191
	s_cbranch_vccz .LBB0_747
	v_max_f32_e32 v32, v191, v191
	v_max_f32_e32 v34, 0, v32
	v_exp_f32_e64 v191, -v34
	s_and_saveexec_b64 s[50:51], s[46:47]
	ds_write_b32 v190, v191 offset:45056
	s_or_b64 exec, exec, s[50:51]
	v_add_u32_e32 v47, s16, v166
	ds_read_b128 v[192:195], v47 offset:45120
	ds_read_b128 v[196:199], v47 offset:45152
	ds_read_b128 v[200:203], v47 offset:45056
	ds_read_b128 v[204:207], v47 offset:45088
	v_add_f32_e32 v82, v82, v34
	v_xor_b32_e32 v32, 0x80000000, v82
	v_pk_add_f32 v[64:65], v[64:65], v[34:35] op_sel_hi:[1,0] neg_lo:[0,1] neg_hi:[0,1]
	v_pk_add_f32 v[48:49], v[48:49], v[34:35] op_sel_hi:[1,0] neg_lo:[0,1] neg_hi:[0,1]
	v_pk_add_f32 v[66:67], v[66:67], v[34:35] op_sel_hi:[1,0] neg_lo:[0,1] neg_hi:[0,1]
	v_pk_add_f32 v[50:51], v[50:51], v[34:35] op_sel_hi:[1,0] neg_lo:[0,1] neg_hi:[0,1]
	v_pk_add_f32 v[68:69], v[68:69], v[34:35] op_sel_hi:[1,0] neg_lo:[0,1] neg_hi:[0,1]
	v_pk_add_f32 v[52:53], v[52:53], v[34:35] op_sel_hi:[1,0] neg_lo:[0,1] neg_hi:[0,1]
	v_pk_add_f32 v[70:71], v[70:71], v[34:35] op_sel_hi:[1,0] neg_lo:[0,1] neg_hi:[0,1]
	v_pk_add_f32 v[54:55], v[54:55], v[34:35] op_sel_hi:[1,0] neg_lo:[0,1] neg_hi:[0,1]
	v_pk_add_f32 v[72:73], v[72:73], v[34:35] op_sel_hi:[1,0] neg_lo:[0,1] neg_hi:[0,1]
	v_pk_add_f32 v[56:57], v[56:57], v[34:35] op_sel_hi:[1,0] neg_lo:[0,1] neg_hi:[0,1]
	v_pk_add_f32 v[74:75], v[74:75], v[34:35] op_sel_hi:[1,0] neg_lo:[0,1] neg_hi:[0,1]
	v_pk_add_f32 v[58:59], v[58:59], v[34:35] op_sel_hi:[1,0] neg_lo:[0,1] neg_hi:[0,1]
	v_pk_add_f32 v[76:77], v[76:77], v[34:35] op_sel_hi:[1,0] neg_lo:[0,1] neg_hi:[0,1]
	v_pk_add_f32 v[60:61], v[60:61], v[34:35] op_sel_hi:[1,0] neg_lo:[0,1] neg_hi:[0,1]
	v_pk_add_f32 v[78:79], v[78:79], v[34:35] op_sel_hi:[1,0] neg_lo:[0,1] neg_hi:[0,1]
	v_pk_add_f32 v[62:63], v[62:63], v[34:35] op_sel_hi:[1,0] neg_lo:[0,1] neg_hi:[0,1]
	v_mov_b32_e32 v33, v32
	v_mov_b32_e32 v34, v32
	v_mov_b32_e32 v35, v32
	v_mov_b32_e32 v36, v32
	v_mov_b32_e32 v37, v32
	v_mov_b32_e32 v38, v32
	v_mov_b32_e32 v39, v32
	v_mov_b32_e32 v40, v32
	v_mov_b32_e32 v41, v32
	v_mov_b32_e32 v42, v32
	v_mov_b32_e32 v43, v32
	v_mov_b32_e32 v44, v32
	v_mov_b32_e32 v45, v32
	v_mov_b32_e32 v46, v32
	v_mov_b32_e32 v47, v32
	v_mul_f32_e32 v83, v83, v191
	s_waitcnt lgkmcnt(2)
	v_pk_mul_f32 v[12:13], v[12:13], v[196:197]
	v_pk_mul_f32 v[8:9], v[8:9], v[192:193]
	s_waitcnt lgkmcnt(0)
	v_pk_mul_f32 v[4:5], v[4:5], v[204:205]
	v_pk_mul_f32 v[14:15], v[14:15], v[198:199]
	v_pk_mul_f32 v[10:11], v[10:11], v[194:195]
	v_pk_mul_f32 v[6:7], v[6:7], v[206:207]
	v_pk_mul_f32 v[2:3], v[2:3], v[202:203]
	v_pk_mul_f32 v[0:1], v[0:1], v[200:201]
	v_pk_mul_f32 v[28:29], v[28:29], v[196:197]
	v_pk_mul_f32 v[24:25], v[24:25], v[192:193]
	v_pk_mul_f32 v[20:21], v[20:21], v[204:205]
	v_pk_mul_f32 v[30:31], v[30:31], v[198:199]
	v_pk_mul_f32 v[26:27], v[26:27], v[194:195]
	v_pk_mul_f32 v[22:23], v[22:23], v[206:207]
	v_pk_mul_f32 v[18:19], v[18:19], v[202:203]
	v_pk_mul_f32 v[16:17], v[16:17], v[200:201]
.LBB0_747:
	v_exp_f32_e32 v192, v64
	v_exp_f32_e32 v193, v65
	v_exp_f32_e32 v194, v66
	v_exp_f32_e32 v195, v67
	v_exp_f32_e32 v196, v68
	v_exp_f32_e32 v197, v69
	v_exp_f32_e32 v198, v70
	v_exp_f32_e32 v199, v71
	v_cvt_pk_bf16_f32 v64, v192, v193
	v_cvt_pk_bf16_f32 v65, v194, v195
	v_cvt_pk_bf16_f32 v66, v196, v197
	v_cvt_pk_bf16_f32 v67, v198, v199
	v_exp_f32_e32 v72, v72
	v_exp_f32_e32 v73, v73
	v_exp_f32_e32 v74, v74
	v_exp_f32_e32 v75, v75
	v_exp_f32_e32 v76, v76
	v_exp_f32_e32 v77, v77
	v_exp_f32_e32 v78, v78
	v_exp_f32_e32 v79, v79
	s_waitcnt lgkmcnt(1)
	v_mfma_f32_32x32x16_bf16 v[0:15], v[64:67], v[160:163], v[0:15]
	v_cvt_pk_bf16_f32 v68, v72, v73
	v_cvt_pk_bf16_f32 v69, v74, v75
	v_cvt_pk_bf16_f32 v70, v76, v77
	v_cvt_pk_bf16_f32 v71, v78, v79
	v_exp_f32_e32 v200, v48
	v_exp_f32_e32 v201, v49
	v_exp_f32_e32 v52, v52
	v_mfma_f32_32x32x16_bf16 v[16:31], v[64:67], v[156:159], v[16:31]
	v_exp_f32_e32 v64, v50
	v_exp_f32_e32 v65, v51
	v_exp_f32_e32 v53, v53
	v_exp_f32_e32 v66, v54
	v_exp_f32_e32 v67, v55
	v_cvt_pk_bf16_f32 v48, v200, v201
	v_cvt_pk_bf16_f32 v49, v64, v65
	v_mfma_f32_32x32x16_bf16 v[0:15], v[68:71], v[152:155], v[0:15]
	v_cvt_pk_bf16_f32 v50, v52, v53
	v_cvt_pk_bf16_f32 v51, v66, v67
	v_add_f32_e64 v54, v192, 0
	v_add_f32_e64 v55, v193, 0
	v_exp_f32_e32 v56, v56
	v_exp_f32_e32 v57, v57
	v_exp_f32_e32 v58, v58
	v_exp_f32_e32 v59, v59
	v_mfma_f32_32x32x16_bf16 v[16:31], v[68:71], v[148:151], v[16:31]
	v_exp_f32_e32 v60, v60
	v_exp_f32_e32 v61, v61
	v_exp_f32_e32 v62, v62
	v_exp_f32_e32 v63, v63
	v_pk_add_f32 v[54:55], v[200:201], v[54:55]
	s_nop 0
	v_pk_add_f32 v[54:55], v[194:195], v[54:55]
	v_mfma_f32_32x32x16_bf16 v[0:15], v[48:51], v[144:147], v[0:15]
	v_add_f32_e64 v54, v64, v54
	v_add_f32_e64 v55, v65, v55
	v_add_f32_e64 v54, v196, v54
	v_add_f32_e64 v55, v197, v55
	v_add_f32_e64 v64, v52, v54
	v_add_f32_e64 v65, v53, v55
	v_cvt_pk_bf16_f32 v52, v56, v57
	v_cvt_pk_bf16_f32 v53, v58, v59
	v_mfma_f32_32x32x16_bf16 v[16:31], v[48:51], v[140:143], v[16:31]
	v_cvt_pk_bf16_f32 v54, v60, v61
	v_cvt_pk_bf16_f32 v55, v62, v63
	v_add_f32_e64 v48, v198, v64
	v_add_f32_e64 v49, v199, v65
	v_add_f32_e64 v48, v66, v48
	v_add_f32_e64 v49, v67, v49
	v_pk_add_f32 v[48:49], v[72:73], v[48:49]
	v_mfma_f32_32x32x16_bf16 v[0:15], v[52:55], v[136:139], v[0:15]
	v_add_f32_e64 v48, v56, v48
	v_add_f32_e64 v49, v57, v49
	v_add_f32_e64 v48, v74, v48
	v_add_f32_e64 v49, v75, v49
	v_add_f32_e64 v48, v58, v48
	v_add_f32_e64 v49, v59, v49
	v_pk_add_f32 v[48:49], v[76:77], v[48:49]
	v_mfma_f32_32x32x16_bf16 v[16:31], v[52:55], v[132:135], v[16:31]
	v_add_f32_e64 v48, v60, v48
	v_add_f32_e64 v49, v61, v49
	v_add_f32_e64 v48, v78, v48
	v_add_f32_e64 v49, v79, v49
	v_add_f32_e64 v48, v62, v48
	v_add_f32_e64 v49, v63, v49
	v_add_f32_e32 v48, v48, v49
	v_add_f32_e32 v83, v83, v48
.Latt_end:
	s_cmp_eq_u32 s65, s67
	s_waitcnt lgkmcnt(0)
	s_waitcnt vmcnt(0)
	s_barrier
	s_cbranch_scc0 .LBB0_740
	s_branch .Latt_after
.Latt_wonly:
	s_xor_b32 s68, s68, 1
	s_mulk_i32 s68, 0x2400
	v_add_u32_e32 v191, s68, v188
	v_lshl_add_u64 v[172:173], v[172:173], 0, s[18:19]
	ds_write2_b64 v191, v[116:117], v[118:119] offset1:2
	s_branch .Latt_end
.Latt_after:
	s_add_i32 s67, s67, 1
	s_and_b32 s68, s67, 1
	s_cmpk_ge_u32 s64, 0xe0
	s_cbranch_scc1 .Lkdma_done_t
	s_xor_b32 s69, s68, 1
	s_mul_i32 s69, s69, 0x3400
	s_lshl_b32 s50, s64, 6
	s_add_i32 s69, s69, s50
	s_mov_b32 m0, s69
	s_nop 0
	global_load_lds_dwordx4 v[204:205], off
	v_lshl_add_u64 v[204:205], v[204:205], 0, v[220:221]
	s_cmpk_ge_u32 s64, 0xc0
	s_cbranch_scc1 .Lkdma_done_t
	s_add_i32 m0, s69, 0x400
	s_nop 0
	global_load_lds_dwordx4 v[206:207], off
	v_lshl_add_u64 v[206:207], v[206:207], 0, v[222:223]
.Lkdma_done_t:
	s_cmp_ge_i32 s65, s66
	s_cbranch_scc1 .LBB0_757
	s_mul_i32 s50, s68, 0x3400
	v_add_u32_e32 v52, s50, v189
	ds_read_b128 v[48:51], v52
	ds_read_b128 v[108:111], v52 offset:32
	ds_read_b128 v[112:115], v52 offset:6656
	ds_read_b128 v[116:119], v52 offset:6688
	ds_read_b128 v[132:135], v52 offset:64
	ds_read_b128 v[136:139], v52 offset:96
	ds_read_b128 v[140:143], v52 offset:6720
	ds_read_b128 v[144:147], v52 offset:6752
	ds_read_b128 v[148:151], v52 offset:128
	ds_read_b128 v[152:155], v52 offset:160
	ds_read_b128 v[156:159], v52 offset:6784
	ds_read_b128 v[160:163], v52 offset:6816
	s_waitcnt lgkmcnt(11)
	v_mfma_f32_32x32x16_bf16 v[64:79], v[48:51], v[104:107], v[32:47]
	s_mul_i32 s50, s68, 0x2400
	v_add_u32_e32 v80, s50, v165
	s_waitcnt lgkmcnt(9)
	v_mfma_f32_32x32x16_bf16 v[48:63], v[112:115], v[104:107], v[32:47]
	v_mfma_f32_32x32x16_bf16 v[64:79], v[108:111], v[100:103], v[64:79]
	v_add_u32_e32 v108, 0x6800, v80
	v_add_u32_e32 v80, 0x7800, v80
	s_waitcnt lgkmcnt(8)
	v_mfma_f32_32x32x16_bf16 v[48:63], v[116:119], v[100:103], v[48:63]
	s_waitcnt lgkmcnt(7)
	v_mfma_f32_32x32x16_bf16 v[64:79], v[132:135], v[96:99], v[64:79]
	s_waitcnt lgkmcnt(5)
	v_mfma_f32_32x32x16_bf16 v[48:63], v[140:143], v[96:99], v[48:63]
	ds_read_b128 v[140:143], v108 offset:32
	v_mfma_f32_32x32x16_bf16 v[64:79], v[136:139], v[92:95], v[64:79]
	s_waitcnt lgkmcnt(5)
	v_mfma_f32_32x32x16_bf16 v[48:63], v[144:147], v[92:95], v[48:63]
	s_waitcnt lgkmcnt(4)
	v_mfma_f32_32x32x16_bf16 v[64:79], v[148:151], v[88:91], v[64:79]
	ds_read_b128 v[148:151], v108
	ds_read_b128 v[144:147], v80 offset:512
	ds_read_b128 v[136:139], v80 offset:544
	ds_read_b128 v[132:135], v108 offset:64
	ds_read_b128 v[116:119], v80 offset:576
	ds_read_b128 v[112:115], v108 offset:96
	ds_read_b128 v[108:111], v80 offset:608
	s_waitcnt lgkmcnt(9)
	v_mfma_f32_32x32x16_bf16 v[48:63], v[156:159], v[88:91], v[48:63]
	v_mfma_f32_32x32x16_bf16 v[64:79], v[152:155], v[84:87], v[64:79]
	s_waitcnt lgkmcnt(8)
	v_mfma_f32_32x32x16_bf16 v[48:63], v[160:163], v[84:87], v[48:63]
	s_nop 9
	v_max_f32_e32 v80, v65, v65
	v_max_f32_e32 v152, v64, v64
	v_max_f32_e32 v80, v152, v80
	v_max3_f32 v152, v66, v67, v49
	v_max3_f32 v80, v80, v48, v50
	v_max3_f32 v80, v80, v51, v68
	v_max3_f32 v152, v152, v70, v71
	v_max3_f32 v80, v80, v69, v52
	v_max3_f32 v152, v152, v54, v55
	v_max3_f32 v80, v80, v53, v72
	v_max3_f32 v152, v152, v74, v75
	v_max3_f32 v80, v80, v73, v56
	v_max3_f32 v152, v152, v58, v59
	v_max3_f32 v80, v80, v57, v76
	v_max3_f32 v152, v152, v78, v79
	v_max3_f32 v80, v80, v77, v60
	v_max3_f32 v152, v152, v62, v63
	v_and_b32_e32 v153, 64, v183
	v_max3_f32 v80, v80, v61, v152
	v_xor_b32_e32 v152, 32, v183
	v_add_u32_e32 v153, 64, v153
	v_cmp_lt_i32_e32 vcc, v152, v153
	s_nop 1
	v_cndmask_b32_e32 v152, v183, v152, vcc
	v_lshlrev_b32_e32 v152, 2, v152
	ds_bpermute_b32 v152, v152, v80
	s_waitcnt lgkmcnt(0)
	v_max_f32_e32 v152, v152, v152
	v_max_f32_e32 v80, v80, v152
	v_cmp_lt_f32_e32 vcc, s3, v80
	s_cbranch_vccz .LBB0_756
	v_max_f32_e32 v32, v80, v80
	v_max_f32_e32 v34, 0, v32
	v_exp_f32_e64 v80, -v34
	s_and_saveexec_b64 s[50:51], s[46:47]
	ds_write_b32 v190, v80 offset:45056
	s_or_b64 exec, exec, s[50:51]
	v_add_u32_e32 v47, s16, v166
	ds_read_b128 v[152:155], v47 offset:45120
	ds_read_b128 v[156:159], v47 offset:45152
	ds_read_b128 v[160:163], v47 offset:45056
	ds_read_b128 v[168:171], v47 offset:45088
	v_add_f32_e32 v32, v82, v34
	v_xor_b32_e32 v32, 0x80000000, v32
	v_pk_add_f32 v[64:65], v[64:65], v[34:35] op_sel_hi:[1,0] neg_lo:[0,1] neg_hi:[0,1]
	v_pk_add_f32 v[48:49], v[48:49], v[34:35] op_sel_hi:[1,0] neg_lo:[0,1] neg_hi:[0,1]
	v_pk_add_f32 v[66:67], v[66:67], v[34:35] op_sel_hi:[1,0] neg_lo:[0,1] neg_hi:[0,1]
	v_pk_add_f32 v[50:51], v[50:51], v[34:35] op_sel_hi:[1,0] neg_lo:[0,1] neg_hi:[0,1]
	v_pk_add_f32 v[68:69], v[68:69], v[34:35] op_sel_hi:[1,0] neg_lo:[0,1] neg_hi:[0,1]
	v_pk_add_f32 v[52:53], v[52:53], v[34:35] op_sel_hi:[1,0] neg_lo:[0,1] neg_hi:[0,1]
	v_pk_add_f32 v[70:71], v[70:71], v[34:35] op_sel_hi:[1,0] neg_lo:[0,1] neg_hi:[0,1]
	v_pk_add_f32 v[54:55], v[54:55], v[34:35] op_sel_hi:[1,0] neg_lo:[0,1] neg_hi:[0,1]
	v_pk_add_f32 v[72:73], v[72:73], v[34:35] op_sel_hi:[1,0] neg_lo:[0,1] neg_hi:[0,1]
	v_pk_add_f32 v[56:57], v[56:57], v[34:35] op_sel_hi:[1,0] neg_lo:[0,1] neg_hi:[0,1]
	v_pk_add_f32 v[74:75], v[74:75], v[34:35] op_sel_hi:[1,0] neg_lo:[0,1] neg_hi:[0,1]
	v_pk_add_f32 v[58:59], v[58:59], v[34:35] op_sel_hi:[1,0] neg_lo:[0,1] neg_hi:[0,1]
	v_pk_add_f32 v[76:77], v[76:77], v[34:35] op_sel_hi:[1,0] neg_lo:[0,1] neg_hi:[0,1]
	v_pk_add_f32 v[60:61], v[60:61], v[34:35] op_sel_hi:[1,0] neg_lo:[0,1] neg_hi:[0,1]
	v_pk_add_f32 v[78:79], v[78:79], v[34:35] op_sel_hi:[1,0] neg_lo:[0,1] neg_hi:[0,1]
	v_pk_add_f32 v[62:63], v[62:63], v[34:35] op_sel_hi:[1,0] neg_lo:[0,1] neg_hi:[0,1]
	v_mov_b32_e32 v33, v32
	v_mov_b32_e32 v34, v32
	v_mov_b32_e32 v35, v32
	v_mov_b32_e32 v36, v32
	v_mov_b32_e32 v37, v32
	v_mov_b32_e32 v38, v32
	v_mov_b32_e32 v39, v32
	v_mov_b32_e32 v40, v32
	v_mov_b32_e32 v41, v32
	v_mov_b32_e32 v42, v32
	v_mov_b32_e32 v43, v32
	v_mov_b32_e32 v44, v32
	v_mov_b32_e32 v45, v32
	v_mov_b32_e32 v46, v32
	v_mov_b32_e32 v47, v32
	v_mul_f32_e32 v83, v83, v80
	s_waitcnt lgkmcnt(2)
	v_pk_mul_f32 v[12:13], v[12:13], v[156:157]
	v_pk_mul_f32 v[8:9], v[8:9], v[152:153]
	s_waitcnt lgkmcnt(0)
	v_pk_mul_f32 v[4:5], v[4:5], v[168:169]
	v_pk_mul_f32 v[14:15], v[14:15], v[158:159]
	v_pk_mul_f32 v[10:11], v[10:11], v[154:155]
	v_pk_mul_f32 v[6:7], v[6:7], v[170:171]
	v_pk_mul_f32 v[2:3], v[2:3], v[162:163]
	v_pk_mul_f32 v[0:1], v[0:1], v[160:161]
	v_pk_mul_f32 v[28:29], v[28:29], v[156:157]
	v_pk_mul_f32 v[24:25], v[24:25], v[152:153]
	v_pk_mul_f32 v[20:21], v[20:21], v[168:169]
	v_pk_mul_f32 v[30:31], v[30:31], v[158:159]
	v_pk_mul_f32 v[26:27], v[26:27], v[154:155]
	v_pk_mul_f32 v[22:23], v[22:23], v[170:171]
	v_pk_mul_f32 v[18:19], v[18:19], v[162:163]
	v_pk_mul_f32 v[16:17], v[16:17], v[160:161]

.LBB0_757:
	s_xor_b32 s68, s68, 1
	s_mul_i32 s69, s68, 0x3400
	v_add_u32_e32 v48, s69, v187
	s_waitcnt vmcnt(1)
	s_nop 0
	s_and_saveexec_b64 s[50:51], s[44:45]
	v_add_u32_e32 v48, s69, v167
	s_nop 0
	s_or_b64 exec, exec, s[50:51]
	s_mulk_i32 s68, 0x2400
	v_add_u32_e32 v48, s68, v188
	s_cmp_ge_i32 s67, s66
	s_waitcnt vmcnt(0)
	ds_write2_b64 v48, v[128:129], v[130:131] offset1:2
	s_waitcnt lgkmcnt(0)
	s_barrier
	s_cbranch_scc1 .LBB0_765
	s_and_b32 s44, s65, 1
	s_mul_i32 s45, s44, 0x3400
	v_add_u32_e32 v48, s45, v189
	ds_read_b128 v[64:67], v48
	ds_read_b128 v[68:71], v48 offset:32
	ds_read_b128 v[72:75], v48 offset:6656
	ds_read_b128 v[76:79], v48 offset:6688
	ds_read_b128 v[108:111], v48 offset:64
	ds_read_b128 v[112:115], v48 offset:96
	ds_read_b128 v[116:119], v48 offset:6720
	ds_read_b128 v[120:123], v48 offset:6752
	ds_read_b128 v[124:127], v48 offset:128
	ds_read_b128 v[128:131], v48 offset:160
	ds_read_b128 v[132:135], v48 offset:6784
	ds_read_b128 v[136:139], v48 offset:6816
	s_mulk_i32 s44, 0x2400
	s_waitcnt lgkmcnt(11)
	v_mfma_f32_32x32x16_bf16 v[48:63], v[64:67], v[104:107], v[32:47]
	v_add_u32_e32 v64, s44, v165
	v_add_u32_e32 v65, 0x6800, v64
	v_add_u32_e32 v64, 0x7800, v64
	s_waitcnt lgkmcnt(9)
	v_mfma_f32_32x32x16_bf16 v[32:47], v[72:75], v[104:107], v[32:47]
	v_mfma_f32_32x32x16_bf16 v[48:63], v[68:71], v[100:103], v[48:63]
	s_waitcnt lgkmcnt(8)
	v_mfma_f32_32x32x16_bf16 v[32:47], v[76:79], v[100:103], v[32:47]
	ds_read_b128 v[100:103], v65
	s_waitcnt lgkmcnt(8)
	v_mfma_f32_32x32x16_bf16 v[48:63], v[108:111], v[96:99], v[48:63]
	s_waitcnt lgkmcnt(6)
	v_mfma_f32_32x32x16_bf16 v[32:47], v[116:119], v[96:99], v[32:47]
	v_mfma_f32_32x32x16_bf16 v[48:63], v[112:115], v[92:95], v[48:63]
	s_waitcnt lgkmcnt(5)
	v_mfma_f32_32x32x16_bf16 v[32:47], v[120:123], v[92:95], v[32:47]
	ds_read_b128 v[92:95], v65 offset:32
	s_waitcnt lgkmcnt(5)
	v_mfma_f32_32x32x16_bf16 v[48:63], v[124:127], v[88:91], v[48:63]
	s_waitcnt lgkmcnt(3)
	v_mfma_f32_32x32x16_bf16 v[32:47], v[132:135], v[88:91], v[32:47]
	ds_read_b128 v[96:99], v64 offset:512
	ds_read_b128 v[88:91], v64 offset:544
	ds_read_b128 v[76:79], v65 offset:64
	ds_read_b128 v[72:75], v64 offset:576
	ds_read_b128 v[68:71], v65 offset:96
	ds_read_b128 v[64:67], v64 offset:608
	v_mfma_f32_32x32x16_bf16 v[48:63], v[128:131], v[84:87], v[48:63]
	s_waitcnt lgkmcnt(8)
	v_mfma_f32_32x32x16_bf16 v[32:47], v[136:139], v[84:87], v[32:47]
	s_nop 9
	v_max_f32_e32 v80, v49, v49
	v_max_f32_e32 v82, v48, v48
	v_max_f32_e32 v80, v82, v80
	v_max3_f32 v82, v50, v51, v33
	v_max3_f32 v80, v80, v32, v34
	v_max3_f32 v80, v80, v35, v52
	v_max3_f32 v82, v82, v54, v55
	v_max3_f32 v80, v80, v53, v36
	v_max3_f32 v82, v82, v38, v39
	v_max3_f32 v80, v80, v37, v56
	v_max3_f32 v82, v82, v58, v59
	v_max3_f32 v80, v80, v57, v40
	v_max3_f32 v82, v82, v42, v43
	v_max3_f32 v80, v80, v41, v60
	v_max3_f32 v82, v82, v62, v63
	v_max3_f32 v80, v80, v61, v44
	v_max3_f32 v82, v82, v46, v47
	v_and_b32_e32 v84, 64, v183
	v_max3_f32 v80, v80, v45, v82
	v_xor_b32_e32 v82, 32, v183
	v_add_u32_e32 v84, 64, v84
	v_cmp_lt_i32_e32 vcc, v82, v84
	s_nop 1
	v_cndmask_b32_e32 v82, v183, v82, vcc
	v_lshlrev_b32_e32 v82, 2, v82
	ds_bpermute_b32 v82, v82, v80
	s_waitcnt lgkmcnt(0)
	v_max_f32_e32 v82, v82, v82
	v_max_f32_e32 v80, v80, v82
	v_cmp_lt_f32_e32 vcc, s3, v80
	s_cbranch_vccz .LBB0_764
	v_max_f32_e32 v80, v80, v80
	v_max_f32_e32 v80, 0, v80
	v_exp_f32_e64 v82, -v80
	s_and_saveexec_b64 s[44:45], s[46:47]
	ds_write_b32 v190, v82 offset:45056
	s_or_b64 exec, exec, s[44:45]
	v_pk_add_f32 v[48:49], v[48:49], v[80:81] op_sel_hi:[1,0] neg_lo:[0,1] neg_hi:[0,1]
	v_pk_add_f32 v[32:33], v[32:33], v[80:81] op_sel_hi:[1,0] neg_lo:[0,1] neg_hi:[0,1]
	v_pk_add_f32 v[50:51], v[50:51], v[80:81] op_sel_hi:[1,0] neg_lo:[0,1] neg_hi:[0,1]
	v_pk_add_f32 v[34:35], v[34:35], v[80:81] op_sel_hi:[1,0] neg_lo:[0,1] neg_hi:[0,1]
	v_pk_add_f32 v[52:53], v[52:53], v[80:81] op_sel_hi:[1,0] neg_lo:[0,1] neg_hi:[0,1]
	v_pk_add_f32 v[36:37], v[36:37], v[80:81] op_sel_hi:[1,0] neg_lo:[0,1] neg_hi:[0,1]
	v_pk_add_f32 v[54:55], v[54:55], v[80:81] op_sel_hi:[1,0] neg_lo:[0,1] neg_hi:[0,1]
	v_pk_add_f32 v[38:39], v[38:39], v[80:81] op_sel_hi:[1,0] neg_lo:[0,1] neg_hi:[0,1]
	v_pk_add_f32 v[56:57], v[56:57], v[80:81] op_sel_hi:[1,0] neg_lo:[0,1] neg_hi:[0,1]
	v_pk_add_f32 v[40:41], v[40:41], v[80:81] op_sel_hi:[1,0] neg_lo:[0,1] neg_hi:[0,1]
	v_pk_add_f32 v[58:59], v[58:59], v[80:81] op_sel_hi:[1,0] neg_lo:[0,1] neg_hi:[0,1]
	v_pk_add_f32 v[42:43], v[42:43], v[80:81] op_sel_hi:[1,0] neg_lo:[0,1] neg_hi:[0,1]
	v_pk_add_f32 v[60:61], v[60:61], v[80:81] op_sel_hi:[1,0] neg_lo:[0,1] neg_hi:[0,1]
	v_pk_add_f32 v[44:45], v[44:45], v[80:81] op_sel_hi:[1,0] neg_lo:[0,1] neg_hi:[0,1]
	v_pk_add_f32 v[62:63], v[62:63], v[80:81] op_sel_hi:[1,0] neg_lo:[0,1] neg_hi:[0,1]
	v_pk_add_f32 v[46:47], v[46:47], v[80:81] op_sel_hi:[1,0] neg_lo:[0,1] neg_hi:[0,1]
	v_add_u32_e32 v80, s16, v166
	ds_read_b128 v[84:87], v80 offset:45056
	ds_read_b128 v[104:107], v80 offset:45088
	ds_read_b128 v[108:111], v80 offset:45120
	ds_read_b128 v[112:115], v80 offset:45152
	v_mul_f32_e32 v83, v83, v82
	s_waitcnt lgkmcnt(3)
	v_pk_mul_f32 v[2:3], v[2:3], v[86:87]
	s_waitcnt lgkmcnt(2)
	v_pk_mul_f32 v[4:5], v[4:5], v[104:105]
	s_waitcnt lgkmcnt(1)
	v_pk_mul_f32 v[8:9], v[8:9], v[108:109]
	s_waitcnt lgkmcnt(0)
	v_pk_mul_f32 v[12:13], v[12:13], v[112:113]
	v_pk_mul_f32 v[14:15], v[14:15], v[114:115]
	v_pk_mul_f32 v[10:11], v[10:11], v[110:111]
	v_pk_mul_f32 v[6:7], v[6:7], v[106:107]
	v_pk_mul_f32 v[0:1], v[0:1], v[84:85]
	v_pk_mul_f32 v[28:29], v[28:29], v[112:113]
	v_pk_mul_f32 v[24:25], v[24:25], v[108:109]
	v_pk_mul_f32 v[20:21], v[20:21], v[104:105]
	v_pk_mul_f32 v[30:31], v[30:31], v[114:115]
	v_pk_mul_f32 v[26:27], v[26:27], v[110:111]
	v_pk_mul_f32 v[22:23], v[22:23], v[106:107]
	v_pk_mul_f32 v[18:19], v[18:19], v[86:87]
	v_pk_mul_f32 v[16:17], v[16:17], v[84:85]
